# grid barrier: issue the acquire-side L1 invalidate at arrival (overlapped with the arrival atomic / wait) instead of after release
# speedup vs baseline: 1.0040x; 1.0040x over previous
; __device__ __forceinline__ unsigned xb_add(unsigned* p, unsigned v) { return __hip_atomic_fetch_add(p, v, __ATOMIC_RELAXED, __HIP_MEMORY_SCOPE_AGENT); }
; __device__ __forceinline__ void xcd_barrier(const XcdBarrier& b) {
;     ...
;         const unsigned old = xb_add(&bar[XB_XSUB(b.x)], 1u);
;         const unsigned gen = old / nloc;
.LBB0_59:
	s_mov_b64 s[12:13], exec
	s_lshl_b32 s3, s3, 8
	v_mbcnt_lo_u32_b32 v1, s12, 0
	s_add_u32 s6, s8, s3
	v_mbcnt_hi_u32_b32 v1, s13, v1
	s_addc_u32 s7, s9, 0
	v_cmp_eq_u32_e32 vcc, 0, v1
	s_and_saveexec_b64 s[8:9], vcc
	s_cbranch_execz .LBB0_61
	s_bcnt1_i32_b64 s3, s[12:13]
	v_mov_b32_e32 v3, 0x1000
	v_mov_b32_e32 v4, s3
	global_atomic_add v3, v3, v4, s[6:7] offset:1024 sc0
	buffer_inv sc1

; __device__ __forceinline__ unsigned xb_ld(unsigned* p)              { return __hip_atomic_load(p, __ATOMIC_RELAXED, __HIP_MEMORY_SCOPE_AGENT); }
; #define XB_SPIN(cond, bar) do { unsigned _sp = 0; while (cond) { __builtin_amdgcn_s_sleep(1); \
;     if ((++_sp & 255u) == 0u) { if (xb_ld(&(bar)[XB_TMO])) break; if (_sp > XB_SPIN_CAP) { atomicAdd(&(bar)[XB_TMO], 1u); break; } } } } while (0)
; __device__ __forceinline__ void xcd_barrier(const XcdBarrier& b) {
;     ...
;             XB_SPIN(xb_ld(&bar[XB_XGEN(b.x)]) == gen, bar);
;             __builtin_amdgcn_fence(__ATOMIC_ACQUIRE, "agent");
;             asm volatile("s_waitcnt vmcnt(0)" ::: "memory");
.LBB0_74:
	s_or_b64 exec, exec, s[12:13]
	s_waitcnt vmcnt(0)
	s_waitcnt vmcnt(0)

; __device__ __forceinline__ unsigned xb_add(unsigned* p, unsigned v) { return __hip_atomic_fetch_add(p, v, __ATOMIC_RELAXED, __HIP_MEMORY_SCOPE_AGENT); }
; __device__ __forceinline__ void xcd_barrier(const XcdBarrier& b) {
;     ...
;             __builtin_amdgcn_fence(__ATOMIC_ACQUIRE, "agent");
;             xb_add(&bar[XB_XGEN(b.x)], 1u);
.LBB0_92:
	s_or_b64 exec, exec, s[8:9]
	s_mov_b64 s[8:9], exec
	v_mbcnt_lo_u32_b32 v0, s8, 0
	v_mbcnt_hi_u32_b32 v0, s9, v0
	v_cmp_eq_u32_e32 vcc, 0, v0
	s_waitcnt vmcnt(0)
	s_and_saveexec_b64 s[12:13], vcc
	s_cbranch_execz .LBB0_94
	s_bcnt1_i32_b64 s3, s[8:9]
	v_mov_b32_e32 v0, 0x2000
	v_mov_b32_e32 v1, s3
	global_atomic_add v0, v1, s[6:7] offset:1024

; __device__ __forceinline__ unsigned xb_add(unsigned* p, unsigned v) { return __hip_atomic_fetch_add(p, v, __ATOMIC_RELAXED, __HIP_MEMORY_SCOPE_AGENT); }
; __device__ __forceinline__ void xcd_barrier(const XcdBarrier& b) {
;     ...
;         const unsigned old = xb_add(&bar[XB_XSUB(b.x)], 1u);
;         const unsigned gen = old / nloc;
.LBB0_157:
	s_mov_b64 s[12:13], exec
	v_readlane_b32 s3, v232, 3
	s_lshl_b32 s3, s3, 8
	v_readlane_b32 s8, v232, 1
	v_mbcnt_lo_u32_b32 v1, s12, 0
	v_readlane_b32 s9, v232, 2
	s_add_u32 s8, s8, s3
	v_mbcnt_hi_u32_b32 v1, s13, v1
	s_addc_u32 s9, s9, 0
	v_cmp_eq_u32_e32 vcc, 0, v1
	s_and_saveexec_b64 s[14:15], vcc
	s_cbranch_execz .LBB0_159
	s_bcnt1_i32_b64 s3, s[12:13]
	v_mov_b32_e32 v3, 0x1000
	v_mov_b32_e32 v4, s3
	global_atomic_add v3, v3, v4, s[8:9] offset:1024 sc0
	buffer_inv sc1

; __device__ __forceinline__ unsigned xb_ld(unsigned* p)              { return __hip_atomic_load(p, __ATOMIC_RELAXED, __HIP_MEMORY_SCOPE_AGENT); }
; #define XB_SPIN(cond, bar) do { unsigned _sp = 0; while (cond) { __builtin_amdgcn_s_sleep(1); \
;     if ((++_sp & 255u) == 0u) { if (xb_ld(&(bar)[XB_TMO])) break; if (_sp > XB_SPIN_CAP) { atomicAdd(&(bar)[XB_TMO], 1u); break; } } } } while (0)
; __device__ __forceinline__ void xcd_barrier(const XcdBarrier& b) {
;     ...
;             XB_SPIN(xb_ld(&bar[XB_XGEN(b.x)]) == gen, bar);
;             __builtin_amdgcn_fence(__ATOMIC_ACQUIRE, "agent");
;             asm volatile("s_waitcnt vmcnt(0)" ::: "memory");
.LBB0_172:
	s_or_b64 exec, exec, s[14:15]
	s_waitcnt vmcnt(0)
	s_waitcnt vmcnt(0)

; __device__ __forceinline__ unsigned xb_add(unsigned* p, unsigned v) { return __hip_atomic_fetch_add(p, v, __ATOMIC_RELAXED, __HIP_MEMORY_SCOPE_AGENT); }
; __device__ __forceinline__ void xcd_barrier(const XcdBarrier& b) {
;     ...
;             __builtin_amdgcn_fence(__ATOMIC_ACQUIRE, "agent");
;             xb_add(&bar[XB_XGEN(b.x)], 1u);
.LBB0_190:
	s_or_b64 exec, exec, s[12:13]
	s_mov_b64 s[12:13], exec
	v_mbcnt_lo_u32_b32 v0, s12, 0
	v_mbcnt_hi_u32_b32 v0, s13, v0
	v_cmp_eq_u32_e32 vcc, 0, v0
	s_waitcnt vmcnt(0)
	s_and_saveexec_b64 s[14:15], vcc
	s_cbranch_execz .LBB0_192
	s_bcnt1_i32_b64 s3, s[12:13]
	v_mov_b32_e32 v0, 0x2000
	v_mov_b32_e32 v1, s3
	global_atomic_add v0, v1, s[8:9] offset:1024

; __device__ __forceinline__ unsigned xb_add(unsigned* p, unsigned v) { return __hip_atomic_fetch_add(p, v, __ATOMIC_RELAXED, __HIP_MEMORY_SCOPE_AGENT); }
; __device__ __forceinline__ void xcd_barrier(const XcdBarrier& b) {
;     ...
;         const unsigned old = xb_add(&bar[XB_XSUB(b.x)], 1u);
;         const unsigned gen = old / nloc;
.LBB0_236:
	s_mov_b64 s[8:9], exec
	s_lshl_b32 s6, s62, 8
	v_mbcnt_lo_u32_b32 v1, s8, 0
	s_add_u32 s6, s18, s6
	v_mbcnt_hi_u32_b32 v1, s9, v1
	s_addc_u32 s7, s19, 0
	v_cmp_eq_u32_e32 vcc, 0, v1
	s_and_saveexec_b64 s[22:23], vcc
	s_cbranch_execz .LBB0_238
	s_bcnt1_i32_b64 s8, s[8:9]
	v_mov_b32_e32 v3, 0x1000
	v_mov_b32_e32 v4, s8
	global_atomic_add v3, v3, v4, s[6:7] offset:1024 sc0
	buffer_inv sc1

; __device__ __forceinline__ unsigned xb_ld(unsigned* p)              { return __hip_atomic_load(p, __ATOMIC_RELAXED, __HIP_MEMORY_SCOPE_AGENT); }
; #define XB_SPIN(cond, bar) do { unsigned _sp = 0; while (cond) { __builtin_amdgcn_s_sleep(1); \
;     if ((++_sp & 255u) == 0u) { if (xb_ld(&(bar)[XB_TMO])) break; if (_sp > XB_SPIN_CAP) { atomicAdd(&(bar)[XB_TMO], 1u); break; } } } } while (0)
; __device__ __forceinline__ void xcd_barrier(const XcdBarrier& b) {
;     ...
;             XB_SPIN(xb_ld(&bar[XB_XGEN(b.x)]) == gen, bar);
;             __builtin_amdgcn_fence(__ATOMIC_ACQUIRE, "agent");
;             asm volatile("s_waitcnt vmcnt(0)" ::: "memory");
.LBB0_251:
	s_or_b64 exec, exec, s[22:23]
	s_waitcnt vmcnt(0)
	s_waitcnt vmcnt(0)

; __device__ __forceinline__ unsigned xb_add(unsigned* p, unsigned v) { return __hip_atomic_fetch_add(p, v, __ATOMIC_RELAXED, __HIP_MEMORY_SCOPE_AGENT); }
; __device__ __forceinline__ void xcd_barrier(const XcdBarrier& b) {
;     ...
;             __builtin_amdgcn_fence(__ATOMIC_ACQUIRE, "agent");
;             xb_add(&bar[XB_XGEN(b.x)], 1u);
.LBB0_269:
	s_or_b64 exec, exec, s[8:9]
	s_mov_b64 s[8:9], exec
	v_mbcnt_lo_u32_b32 v0, s8, 0
	v_mbcnt_hi_u32_b32 v0, s9, v0
	v_cmp_eq_u32_e32 vcc, 0, v0
	s_waitcnt vmcnt(0)
	s_and_saveexec_b64 s[22:23], vcc
	s_cbranch_execz .LBB0_271
	s_bcnt1_i32_b64 s8, s[8:9]
	v_mov_b32_e32 v0, 0x2000
	v_mov_b32_e32 v1, s8
	global_atomic_add v0, v1, s[6:7] offset:1024

; __device__ __forceinline__ unsigned xb_add(unsigned* p, unsigned v) { return __hip_atomic_fetch_add(p, v, __ATOMIC_RELAXED, __HIP_MEMORY_SCOPE_AGENT); }
; __device__ __forceinline__ void xcd_barrier(const XcdBarrier& b) {
;     ...
;         const unsigned old = xb_add(&bar[XB_XSUB(b.x)], 1u);
;         const unsigned gen = old / nloc;
.LBB0_304:
	s_mov_b64 s[8:9], exec
	s_lshl_b32 s3, s62, 8
	v_mbcnt_lo_u32_b32 v1, s8, 0
	s_add_u32 s6, s18, s3
	v_mbcnt_hi_u32_b32 v1, s9, v1
	s_addc_u32 s7, s19, 0
	v_cmp_eq_u32_e32 vcc, 0, v1
	s_and_saveexec_b64 s[26:27], vcc
	s_cbranch_execz .LBB0_306
	s_bcnt1_i32_b64 s3, s[8:9]
	v_mov_b32_e32 v3, 0x1000
	v_mov_b32_e32 v4, s3
	global_atomic_add v3, v3, v4, s[6:7] offset:1024 sc0
	buffer_inv sc1

; __device__ __forceinline__ unsigned xb_ld(unsigned* p)              { return __hip_atomic_load(p, __ATOMIC_RELAXED, __HIP_MEMORY_SCOPE_AGENT); }
; #define XB_SPIN(cond, bar) do { unsigned _sp = 0; while (cond) { __builtin_amdgcn_s_sleep(1); \
;     if ((++_sp & 255u) == 0u) { if (xb_ld(&(bar)[XB_TMO])) break; if (_sp > XB_SPIN_CAP) { atomicAdd(&(bar)[XB_TMO], 1u); break; } } } } while (0)
; __device__ __forceinline__ void xcd_barrier(const XcdBarrier& b) {
;     ...
;             XB_SPIN(xb_ld(&bar[XB_XGEN(b.x)]) == gen, bar);
;             __builtin_amdgcn_fence(__ATOMIC_ACQUIRE, "agent");
;             asm volatile("s_waitcnt vmcnt(0)" ::: "memory");
.LBB0_319:
	s_or_b64 exec, exec, s[26:27]
	s_waitcnt vmcnt(0)
	s_waitcnt vmcnt(0)

; __device__ __forceinline__ unsigned xb_add(unsigned* p, unsigned v) { return __hip_atomic_fetch_add(p, v, __ATOMIC_RELAXED, __HIP_MEMORY_SCOPE_AGENT); }
; __device__ __forceinline__ void xcd_barrier(const XcdBarrier& b) {
;     ...
;             __builtin_amdgcn_fence(__ATOMIC_ACQUIRE, "agent");
;             xb_add(&bar[XB_XGEN(b.x)], 1u);
.LBB0_337:
	s_or_b64 exec, exec, s[8:9]
	s_mov_b64 s[8:9], exec
	v_mbcnt_lo_u32_b32 v0, s8, 0
	v_mbcnt_hi_u32_b32 v0, s9, v0
	v_cmp_eq_u32_e32 vcc, 0, v0
	s_waitcnt vmcnt(0)
	s_and_saveexec_b64 s[26:27], vcc
	s_cbranch_execz .LBB0_339
	s_bcnt1_i32_b64 s3, s[8:9]
	v_mov_b32_e32 v0, 0x2000
	v_mov_b32_e32 v1, s3
	global_atomic_add v0, v1, s[6:7] offset:1024

; __device__ __forceinline__ unsigned xb_add(unsigned* p, unsigned v) { return __hip_atomic_fetch_add(p, v, __ATOMIC_RELAXED, __HIP_MEMORY_SCOPE_AGENT); }
; __device__ __forceinline__ void xcd_barrier(const XcdBarrier& b) {
;     ...
;         const unsigned old = xb_add(&bar[XB_XSUB(b.x)], 1u);
;         const unsigned gen = old / nloc;
.LBB0_363:
	s_mov_b64 s[6:7], exec
	s_lshl_b32 s4, s62, 8
	v_mbcnt_lo_u32_b32 v1, s6, 0
	s_add_u32 s4, s18, s4
	v_mbcnt_hi_u32_b32 v1, s7, v1
	s_addc_u32 s5, s19, 0
	v_cmp_eq_u32_e32 vcc, 0, v1
	s_and_saveexec_b64 s[8:9], vcc
	s_cbranch_execz .LBB0_365
	s_bcnt1_i32_b64 s6, s[6:7]
	v_mov_b32_e32 v3, 0x1000
	v_mov_b32_e32 v4, s6
	global_atomic_add v3, v3, v4, s[4:5] offset:1024 sc0
	buffer_inv sc1

; __device__ __forceinline__ unsigned xb_ld(unsigned* p)              { return __hip_atomic_load(p, __ATOMIC_RELAXED, __HIP_MEMORY_SCOPE_AGENT); }
; #define XB_SPIN(cond, bar) do { unsigned _sp = 0; while (cond) { __builtin_amdgcn_s_sleep(1); \
;     if ((++_sp & 255u) == 0u) { if (xb_ld(&(bar)[XB_TMO])) break; if (_sp > XB_SPIN_CAP) { atomicAdd(&(bar)[XB_TMO], 1u); break; } } } } while (0)
; __device__ __forceinline__ void xcd_barrier(const XcdBarrier& b) {
;     ...
;             XB_SPIN(xb_ld(&bar[XB_XGEN(b.x)]) == gen, bar);
;             __builtin_amdgcn_fence(__ATOMIC_ACQUIRE, "agent");
;             asm volatile("s_waitcnt vmcnt(0)" ::: "memory");
.LBB0_378:
	s_or_b64 exec, exec, s[8:9]
	s_waitcnt vmcnt(0)
	s_waitcnt vmcnt(0)

; __device__ __forceinline__ unsigned xb_add(unsigned* p, unsigned v) { return __hip_atomic_fetch_add(p, v, __ATOMIC_RELAXED, __HIP_MEMORY_SCOPE_AGENT); }
; __device__ __forceinline__ void xcd_barrier(const XcdBarrier& b) {
;     ...
;             __builtin_amdgcn_fence(__ATOMIC_ACQUIRE, "agent");
;             xb_add(&bar[XB_XGEN(b.x)], 1u);
.LBB0_396:
	s_or_b64 exec, exec, s[6:7]
	s_mov_b64 s[6:7], exec
	v_mbcnt_lo_u32_b32 v0, s6, 0
	v_mbcnt_hi_u32_b32 v0, s7, v0
	v_cmp_eq_u32_e32 vcc, 0, v0
	s_waitcnt vmcnt(0)
	s_and_saveexec_b64 s[8:9], vcc
	s_cbranch_execz .LBB0_398
	s_bcnt1_i32_b64 s6, s[6:7]
	v_mov_b32_e32 v0, 0x2000
	v_mov_b32_e32 v1, s6
	global_atomic_add v0, v1, s[4:5] offset:1024

; __device__ __forceinline__ unsigned xb_add(unsigned* p, unsigned v) { return __hip_atomic_fetch_add(p, v, __ATOMIC_RELAXED, __HIP_MEMORY_SCOPE_AGENT); }
; __device__ __forceinline__ void xcd_barrier(const XcdBarrier& b) {
;     ...
;         const unsigned old = xb_add(&bar[XB_XSUB(b.x)], 1u);
;         const unsigned gen = old / nloc;
.LBB0_431:
	s_mov_b64 s[6:7], exec
	v_readlane_b32 s4, v232, 3
	s_lshl_b32 s4, s4, 8
	v_readlane_b32 s8, v232, 1
	v_mbcnt_lo_u32_b32 v1, s6, 0
	v_readlane_b32 s9, v232, 2
	s_add_u32 s4, s8, s4
	v_mbcnt_hi_u32_b32 v1, s7, v1
	s_addc_u32 s5, s9, 0
	v_cmp_eq_u32_e32 vcc, 0, v1
	s_and_saveexec_b64 s[8:9], vcc
	s_cbranch_execz .LBB0_433
	s_bcnt1_i32_b64 s6, s[6:7]
	v_mov_b32_e32 v3, 0x1000
	v_mov_b32_e32 v4, s6
	global_atomic_add v3, v3, v4, s[4:5] offset:1024 sc0
	buffer_inv sc1

; __device__ __forceinline__ unsigned xb_add(unsigned* p, unsigned v) { return __hip_atomic_fetch_add(p, v, __ATOMIC_RELAXED, __HIP_MEMORY_SCOPE_AGENT); }
; __device__ __forceinline__ void xcd_barrier(const XcdBarrier& b) {
;     ...
;         const unsigned old = xb_add(&bar[XB_XSUB(b.x)], 1u);
;         const unsigned gen = old / nloc;
.LBB0_694:
	s_mov_b64 s[8:9], exec
	s_lshl_b32 s6, s62, 8
	v_mbcnt_lo_u32_b32 v1, s8, 0
	s_add_u32 s6, s18, s6
	v_mbcnt_hi_u32_b32 v1, s9, v1
	s_addc_u32 s7, s19, 0
	v_cmp_eq_u32_e32 vcc, 0, v1
	s_and_saveexec_b64 s[30:31], vcc
	s_cbranch_execz .LBB0_696
	s_bcnt1_i32_b64 s8, s[8:9]
	v_mov_b32_e32 v3, 0x1000
	v_mov_b32_e32 v4, s8
	global_atomic_add v3, v3, v4, s[6:7] offset:1024 sc0
	buffer_inv sc1

; __device__ __forceinline__ unsigned xb_ld(unsigned* p)              { return __hip_atomic_load(p, __ATOMIC_RELAXED, __HIP_MEMORY_SCOPE_AGENT); }
; #define XB_SPIN(cond, bar) do { unsigned _sp = 0; while (cond) { __builtin_amdgcn_s_sleep(1); \
;     if ((++_sp & 255u) == 0u) { if (xb_ld(&(bar)[XB_TMO])) break; if (_sp > XB_SPIN_CAP) { atomicAdd(&(bar)[XB_TMO], 1u); break; } } } } while (0)
; __device__ __forceinline__ void xcd_barrier(const XcdBarrier& b) {
;     ...
;             XB_SPIN(xb_ld(&bar[XB_XGEN(b.x)]) == gen, bar);
;             __builtin_amdgcn_fence(__ATOMIC_ACQUIRE, "agent");
;             asm volatile("s_waitcnt vmcnt(0)" ::: "memory");
.LBB0_709:
	s_or_b64 exec, exec, s[30:31]
	s_waitcnt vmcnt(0)
	s_waitcnt vmcnt(0)

; __device__ __forceinline__ unsigned xb_add(unsigned* p, unsigned v) { return __hip_atomic_fetch_add(p, v, __ATOMIC_RELAXED, __HIP_MEMORY_SCOPE_AGENT); }
; __device__ __forceinline__ void xcd_barrier(const XcdBarrier& b) {
;     ...
;             __builtin_amdgcn_fence(__ATOMIC_ACQUIRE, "agent");
;             xb_add(&bar[XB_XGEN(b.x)], 1u);
.LBB0_727:
	s_or_b64 exec, exec, s[8:9]
	s_mov_b64 s[8:9], exec
	v_mbcnt_lo_u32_b32 v0, s8, 0
	v_mbcnt_hi_u32_b32 v0, s9, v0
	v_cmp_eq_u32_e32 vcc, 0, v0
	s_waitcnt vmcnt(0)
	s_and_saveexec_b64 s[30:31], vcc
	s_cbranch_execz .LBB0_729
	s_bcnt1_i32_b64 s8, s[8:9]
	v_mov_b32_e32 v0, 0x2000
	v_mov_b32_e32 v1, s8
	global_atomic_add v0, v1, s[6:7] offset:1024
